# v118 + grid barrier: the XCD leader issues its L1 invalidate before the L2 write-back (both complete under one wait) instead of after it
# baseline (speedup 1.0000x reference)
.LBB0_166:
	s_andn2_saveexec_b64 s[8:9], s[8:9]
	s_cbranch_execz .LBB0_186
	s_mov_b64 s[8:9], exec
	buffer_inv sc1
	buffer_wbl2 sc1
	s_waitcnt lgkmcnt(0)
	s_waitcnt vmcnt(0)
	v_mbcnt_lo_u32_b32 v1, s8, 0
	v_mbcnt_hi_u32_b32 v1, s9, v1
	v_cmp_eq_u32_e32 vcc, 0, v1
	s_and_saveexec_b64 s[10:11], vcc
	s_cbranch_execz .LBB0_169
	s_bcnt1_i32_b64 s8, s[8:9]
	v_mov_b32_e32 v2, 0x7000
	v_mov_b32_e32 v3, s8
	global_atomic_add v2, v2, v3, s[40:41] offset:1024 sc0

.LBB0_900:
	s_andn2_saveexec_b64 s[10:11], s[10:11]
	s_cbranch_execz .LBB0_920
	s_mov_b64 s[10:11], exec
	buffer_inv sc1
	buffer_wbl2 sc1
	s_waitcnt lgkmcnt(0)
	s_waitcnt vmcnt(0)
	v_mbcnt_lo_u32_b32 v33, s10, 0
	v_mbcnt_hi_u32_b32 v33, s11, v33
	v_cmp_eq_u32_e32 vcc, 0, v33
	s_and_saveexec_b64 s[12:13], vcc
	s_cbranch_execz .LBB0_903
	s_bcnt1_i32_b64 s10, s[10:11]
	v_mov_b32_e32 v36, 0x7000
	v_mov_b32_e32 v37, s10
	global_atomic_add v36, v36, v37, s[40:41] offset:1024 sc0

.LBB0_986:
	s_andn2_saveexec_b64 s[8:9], s[8:9]
	s_cbranch_execz .LBB0_1006
	s_mov_b64 s[8:9], exec
	buffer_inv sc1
	buffer_wbl2 sc1
	s_waitcnt lgkmcnt(0)
	s_waitcnt vmcnt(0)
	v_mbcnt_lo_u32_b32 v1, s8, 0
	v_mbcnt_hi_u32_b32 v1, s9, v1
	v_cmp_eq_u32_e32 vcc, 0, v1
	s_and_saveexec_b64 s[12:13], vcc
	s_cbranch_execz .LBB0_989
	s_bcnt1_i32_b64 s8, s[8:9]
	v_mov_b32_e32 v2, 0x7000
	v_mov_b32_e32 v3, s8
	global_atomic_add v2, v2, v3, s[40:41] offset:1024 sc0

.LBB0_1092:
	s_andn2_saveexec_b64 s[12:13], s[12:13]
	s_cbranch_execz .LBB0_1112
	s_mov_b64 s[12:13], exec
	buffer_inv sc1
	buffer_wbl2 sc1
	s_waitcnt lgkmcnt(0)
	s_waitcnt vmcnt(0)
	v_mbcnt_lo_u32_b32 v1, s12, 0
	v_mbcnt_hi_u32_b32 v1, s13, v1
	v_cmp_eq_u32_e32 vcc, 0, v1
	s_and_saveexec_b64 s[14:15], vcc
	s_cbranch_execz .LBB0_1095
	s_bcnt1_i32_b64 s12, s[12:13]
	v_mov_b32_e32 v2, 0x7000
	v_mov_b32_e32 v3, s12
	global_atomic_add v2, v2, v3, s[40:41] offset:1024 sc0

.LBB0_1319:
	s_andn2_saveexec_b64 s[8:9], s[8:9]
	s_cbranch_execz .LBB0_1339
	s_mov_b64 s[8:9], exec
	buffer_inv sc1
	buffer_wbl2 sc1
	s_waitcnt lgkmcnt(0)
	s_waitcnt vmcnt(0)
	v_mbcnt_lo_u32_b32 v1, s8, 0
	v_mbcnt_hi_u32_b32 v1, s9, v1
	v_cmp_eq_u32_e32 vcc, 0, v1
	s_and_saveexec_b64 s[10:11], vcc
	s_cbranch_execz .LBB0_1322
	s_bcnt1_i32_b64 s3, s[8:9]
	v_mov_b32_e32 v2, 0x7000
	v_mov_b32_e32 v3, s3
	global_atomic_add v2, v2, v3, s[40:41] offset:1024 sc0
